# attention: fourth early K fragment read after the last P.V MFMA, first QK wait moved to the K20 consumer
# baseline (speedup 1.0000x reference)
.Ltb_u1_b:
	s_ashr_i32 s11, s6, 6
	s_lshl_b32 s10, s43, 4
	s_lshl_b32 s26, s11, 2
	v_bfe_u32 v233, v237, 4, 2
	s_and_b32 s60, s10, 0xfffff000
	v_or_b32_e32 v52, s26, v233
	s_waitcnt vmcnt(0)
	v_add_u32_e32 v2, s60, v52
	v_ashrrev_i32_e32 v3, 31, v2
	v_readlane_b32 s18, v252, 31
	v_bitop3_b32 v0, s26, v237, v233 bitop3:0x36
	v_lshlrev_b64 v[2:3], 12, v[2:3]
	v_readlane_b32 s19, v252, 32
	s_and_b32 s46, s43, 15
	s_lshl_b32 s84, s28, 8
	v_lshl_add_u64 v[2:3], s[18:19], 0, v[2:3]
	v_lshlrev_b32_e32 v0, 4, v0
	s_xor_b32 s17, s46, 31
	s_and_b32 s2, s11, 3
	v_lshl_add_u64 v[2:3], v[2:3], 0, s[84:85]
	v_and_b32_e32 v0, 0xf0, v0
	s_lshl_b32 s27, s11, 3
	v_bfe_u32 v53, v237, 3, 3
	s_lshl_b32 s21, s17, 7
	s_lshl_b32 s22, s2, 5
	s_lshl_b32 s18, s28, 7
	v_lshl_add_u64 v[2:3], v[2:3], 0, v[0:1]
	v_or_b32_e32 v0, s27, v53
	s_or_b32 s20, s22, s21
	v_lshrrev_b32_e32 v54, 1, v0
	v_add_u32_e32 v4, s18, v0
	v_and_b32_e32 v235, 31, v237
	v_xor_b32_e32 v6, v54, v237
	v_ashrrev_i32_e32 v5, 31, v4
	v_readlane_b32 s36, v252, 39
	s_or_b32 s10, s20, s60
	v_lshlrev_b64 v[4:5], 15, v[4:5]
	v_readlane_b32 s37, v252, 40
	v_lshlrev_b32_e32 v0, 4, v6
	v_or_b32_e32 v6, s10, v235
	v_lshl_add_u64 v[4:5], s[36:37], 0, v[4:5]
	v_ashrrev_i32_e32 v7, 31, v6
	v_readlane_b32 s36, v252, 17
	s_ashr_i32 s3, s6, 8
	v_lshlrev_b64 v[6:7], 12, v[6:7]
	v_readlane_b32 s37, v252, 18
	s_ashr_i32 s61, s60, 31
	v_bfe_u32 v234, v237, 5, 1
	v_lshl_add_u64 v[6:7], s[36:37], 0, v[6:7]
	s_lshl_b32 s36, s3, 6
	v_lshl_add_u64 v[4:5], s[60:61], 1, v[4:5]
	v_and_b32_e32 v0, 0x70, v0
	v_lshl_add_u64 v[6:7], v[6:7], 0, s[84:85]
	s_ashr_i32 s37, s36, 31
	v_lshl_add_u64 v[4:5], v[4:5], 0, v[0:1]
	v_lshl_add_u64 v[6:7], s[36:37], 1, v[6:7]
	v_lshlrev_b32_e32 v0, 4, v234
	v_lshl_add_u64 v[6:7], v[6:7], 0, v[0:1]
	global_load_dwordx4 v[146:149], v[6:7], off nt
	global_load_dwordx4 v[150:153], v[6:7], off offset:32 nt
	global_load_dwordx4 v[154:157], v[6:7], off offset:64 nt
	global_load_dwordx4 v[158:161], v[6:7], off offset:96 nt
	s_lshl_b32 s11, s11, 10
	s_add_i32 s11, s11, 0
	s_mov_b32 m0, s11
	s_mov_b64 s[36:37], 0x20000
	global_load_lds_dwordx4 v[2:3], off
	v_lshl_add_u64 v[8:9], v[2:3], 0, s[36:37]
	s_add_i32 m0, s11, 0x2000
	s_mov_b64 s[36:37], 0x40000
	global_load_lds_dwordx4 v[8:9], off
	s_add_i32 m0, s11, 0x4000
	v_lshl_add_u64 v[8:9], v[2:3], 0, s[36:37]
	s_mov_b64 s[36:37], 0x60000
	global_load_lds_dwordx4 v[8:9], off
	v_lshl_add_u64 v[8:9], v[2:3], 0, s[36:37]
	s_add_i32 m0, s11, 0x6000
	s_mov_b64 s[36:37], 0x200000
	global_load_lds_dwordx4 v[8:9], off
	s_add_i32 m0, s11, 0xc000
	v_lshl_add_u64 v[8:9], v[4:5], 0, s[36:37]
	global_load_lds_dwordx4 v[4:5], off
	s_add_i32 m0, s11, 0xe000
	s_mov_b64 s[36:37], 0xa0000
	global_load_lds_dwordx4 v[8:9], off
	s_add_i32 m0, s11, 0x8000
	v_lshl_add_u64 v[8:9], v[2:3], 0, s[34:35]
	global_load_lds_dwordx4 v[8:9], off
	v_lshl_add_u64 v[2:3], v[2:3], 0, s[36:37]
	s_add_i32 m0, s11, 0xa000
	s_mov_b64 s[36:37], 0x80
	global_load_lds_dwordx4 v[2:3], off
	s_add_i32 m0, s11, 0x10000
	v_lshl_add_u64 v[2:3], v[4:5], 0, s[36:37]
	s_mov_b64 s[36:37], 0x200080
	global_load_lds_dwordx4 v[2:3], off
	v_lshl_add_u64 v[2:3], v[4:5], 0, s[36:37]
	s_add_i32 m0, s11, 0x12000
	v_and_b32_e32 v0, 19, v237
	global_load_lds_dwordx4 v[2:3], off
	v_lshlrev_b32_e32 v2, 1, v237
	v_lshrrev_b32_e32 v35, 1, v34
	v_and_or_b32 v0, v2, 8, v0
	v_and_b32_e32 v22, 4, v35
	v_or_b32_e32 v2, v0, v22
	v_lshl_or_b32 v45, s3, 3, v234
	v_lshlrev_b32_e32 v44, 8, v2
	v_bitop3_b32 v2, v2, v45, 15 bitop3:0x6c
	v_lshl_add_u32 v239, v2, 4, v44
	s_waitcnt vmcnt(4)
	s_barrier
	v_add_u32_e32 v6, 0, v239
	v_bitop3_b32 v0, v0, 15, v22 bitop3:0xc8
	ds_read_b128 v[2:5], v6
	ds_read_b128 v[18:21], v6 offset:8192
	v_bitop3_b32 v22, v45, v0, 2 bitop3:0x36
	v_lshl_add_u32 v240, v22, 4, v44
	v_add_u32_e32 v40, 0, v240
	ds_read_b128 v[36:39], v40
	s_waitcnt vmcnt(0) lgkmcnt(0)
	v_mfma_f32_32x32x16_bf16 v[2:17], v[2:5], v[146:149], 0
	ds_read_b128 v[40:43], v40 offset:8192
	v_bfe_u32 v34, v34, 1, 3
	v_bitop3_b32 v57, v234, v34, 2 bitop3:0x36
	v_bitop3_b32 v58, v234, v34, 4 bitop3:0x36
	v_bitop3_b32 v59, v234, v34, 6 bitop3:0x36
	s_and_b32 s56, s42, 0xfffff000
	s_add_i32 s26, s26, s56
	v_mfma_f32_32x32x16_bf16 v[18:33], v[18:21], v[146:149], 0
	s_lshr_b32 s16, s43, 4
	s_and_b32 s16, s16, 15
	s_lshl_b32 s36, s16, 7
	s_lshl_b32 s37, s16, 8
	s_add_i32 s27, s27, s36
	s_ashr_i32 s57, s56, 31
	s_lshl_b64 s[44:45], s[56:57], 1
	v_mfma_f32_32x32x16_bf16 v[2:17], v[36:39], v[150:153], v[2:17]
	v_bitop3_b32 v36, v45, v0, 4 bitop3:0x36
	v_lshl_add_u32 v241, v36, 4, v44
	v_add_u32_e32 v46, 0, v241
	ds_read_b128 v[36:39], v46
	v_bitop3_b32 v0, v45, v0, 6 bitop3:0x36
	v_lshl_add_u32 v243, v0, 4, v44
	v_add_u32_e32 v0, 0, v243
	s_waitcnt lgkmcnt(1)
	v_mfma_f32_32x32x16_bf16 v[18:33], v[40:43], v[150:153], v[18:33]
	ds_read_b128 v[40:43], v46 offset:8192
	v_lshlrev_b32_e32 v236, 3, v234
	s_mov_b32 s84, s85
	v_bitop3_b32 v56, v35, v234, 7 bitop3:0x6c
	s_mov_b32 s86, s85
	s_mov_b32 s87, s85
	s_mov_b32 s88, s85
	s_waitcnt lgkmcnt(1)
	v_mfma_f32_32x32x16_bf16 v[2:17], v[36:39], v[154:157], v[2:17]
	ds_read_b128 v[36:39], v0
	s_mov_b32 s89, s85
	s_mov_b32 s90, s85
	s_mov_b32 s91, s85
	s_mov_b32 s92, s85
	s_mov_b32 s93, s85
	s_mov_b32 s94, s85
	s_waitcnt lgkmcnt(1)
	v_mfma_f32_32x32x16_bf16 v[18:33], v[40:43], v[154:157], v[18:33]
	ds_read_b128 v[40:43], v0 offset:8192
	s_mov_b32 s95, s85
	s_mov_b32 s96, s85
	s_mov_b32 s97, s85
	s_mov_b32 s98, s85
	s_mov_b32 s99, s85
	s_lshl_b32 s16, s17, 1
	s_waitcnt lgkmcnt(1)
	v_mfma_f32_32x32x16_bf16 v[2:17], v[36:39], v[158:161], v[2:17]
	v_lshlrev_b32_e32 v55, 7, v235
	s_lshr_b32 s19, s20, 6
	s_add_i32 s17, s16, 2
	s_add_i32 s19, s19, 1
	v_lshl_or_b32 v244, v56, 4, v55
	v_lshl_or_b32 v245, v57, 4, v55
	v_lshl_or_b32 v246, v58, 4, v55
	s_waitcnt lgkmcnt(0)
	v_mfma_f32_32x32x16_bf16 v[18:33], v[40:43], v[158:161], v[18:33]
	s_nop 2
	v_max_f32_e32 v34, v3, v3
	v_lshl_or_b32 v247, v59, 4, v55
	s_mov_b32 s23, 1
	v_and_b32_e32 v238, 63, v237
	s_mov_b32 s31, 0x8000
	s_min_u32 s19, s17, s19
	s_addk_i32 s20, 0xff50
	s_nop 1
	v_max_f32_e32 v0, v19, v19
	v_max_f32_e32 v0, v34, v0
	v_max3_f32 v0, v2, v18, v0
	v_max3_f32 v34, v20, v5, v21
	v_max3_f32 v0, v0, v4, v34
	v_max3_f32 v34, v22, v7, v23
	v_max3_f32 v0, v0, v6, v34
	v_max3_f32 v34, v24, v9, v25
	v_max3_f32 v0, v0, v8, v34
	v_max3_f32 v34, v26, v11, v27
	v_max3_f32 v0, v0, v10, v34
	v_max3_f32 v34, v28, v13, v29
	v_max3_f32 v0, v0, v12, v34
	v_max3_f32 v34, v30, v15, v31
	v_max3_f32 v0, v0, v14, v34
	v_max3_f32 v34, v32, v17, v33
	v_max3_f32 v0, v0, v16, v34
	v_mov_b32_e32 v34, v0
	s_nop 1
	v_permlane32_swap_b32_e32 v0, v34
	v_max_f32_e32 v34, v34, v34
	v_max_f32_e32 v0, v0, v0
	v_max_f32_e32 v213, v0, v34
	v_sub_f32_e32 v0, v2, v213
	v_exp_f32_e32 v60, v0
	v_sub_f32_e32 v0, v18, v213
	v_exp_f32_e32 v61, v0
	v_sub_f32_e32 v0, v3, v213
	v_sub_f32_e32 v2, v19, v213
	v_exp_f32_e32 v0, v0
	v_exp_f32_e32 v2, v2
	v_add_f32_e32 v3, v61, v60
	v_mov_b64_e32 v[34:35], s[84:85]
	v_cvt_pk_bf16_f32 v162, v60, v0
	v_pk_add_f32 v[18:19], v[2:3], v[0:1]
	v_sub_f32_e32 v3, v4, v213
	v_sub_f32_e32 v4, v20, v213
	v_pk_add_f32 v[18:19], v[18:19], v[18:19] op_sel_hi:[0,1]
	v_exp_f32_e32 v62, v4
	v_sub_f32_e32 v4, v5, v213
	v_exp_f32_e32 v3, v3
	v_exp_f32_e32 v18, v4
	v_sub_f32_e32 v4, v21, v213
	v_exp_f32_e32 v4, v4
	v_add_f32_e32 v5, v62, v3
	v_sub_u32_e32 v0, 7, v237
	v_cvt_pk_bf16_f32 v178, v61, v2
	v_pk_add_f32 v[20:21], v[4:5], v[18:19]
	v_sub_f32_e32 v5, v6, v213
	v_sub_f32_e32 v6, v22, v213
	v_pk_add_f32 v[20:21], v[20:21], v[20:21] op_sel_hi:[0,1]
	v_exp_f32_e32 v19, v6
	v_sub_f32_e32 v6, v7, v213
	v_exp_f32_e32 v5, v5
	v_exp_f32_e32 v20, v6
	v_sub_f32_e32 v6, v23, v213
	v_exp_f32_e32 v6, v6
	v_add_f32_e32 v7, v19, v5
	v_and_b32_e32 v0, 3, v0
	v_mov_b32_e32 v2, s33
	v_pk_add_f32 v[22:23], v[6:7], v[20:21]
	v_sub_f32_e32 v7, v8, v213
	v_sub_f32_e32 v8, v24, v213
	v_pk_add_f32 v[22:23], v[22:23], v[22:23] op_sel_hi:[0,1]
	v_exp_f32_e32 v21, v8
	v_sub_f32_e32 v8, v9, v213
	v_exp_f32_e32 v7, v7
	v_exp_f32_e32 v22, v8
	v_sub_f32_e32 v8, v25, v213
	v_exp_f32_e32 v8, v8
	v_add_f32_e32 v9, v21, v7
	s_movk_i32 s33, 0x510
	v_mad_u32_u24 v0, v0, s33, v2
	v_pk_add_f32 v[24:25], v[8:9], v[22:23]
	v_sub_f32_e32 v9, v10, v213
	v_sub_f32_e32 v10, v26, v213
	v_pk_add_f32 v[24:25], v[24:25], v[24:25] op_sel_hi:[0,1]
	v_exp_f32_e32 v23, v10
	v_sub_f32_e32 v10, v11, v213
	v_exp_f32_e32 v9, v9
	v_exp_f32_e32 v24, v10
	v_sub_f32_e32 v10, v27, v213
	v_exp_f32_e32 v10, v10
	v_add_f32_e32 v11, v23, v9
	v_or_b32_e32 v2, s26, v233
	v_cvt_pk_bf16_f32 v163, v3, v18
	v_pk_add_f32 v[26:27], v[10:11], v[24:25]
	v_sub_f32_e32 v11, v12, v213
	v_sub_f32_e32 v12, v28, v213
	v_pk_add_f32 v[26:27], v[26:27], v[26:27] op_sel_hi:[0,1]
	v_exp_f32_e32 v25, v12
	v_sub_f32_e32 v12, v13, v213
	v_exp_f32_e32 v11, v11
	v_exp_f32_e32 v26, v12
	v_sub_f32_e32 v12, v29, v213
	v_exp_f32_e32 v12, v12
	v_add_f32_e32 v13, v25, v11
	v_ashrrev_i32_e32 v3, 31, v2
	v_lshlrev_b64 v[214:215], 12, v[2:3]
	v_pk_add_f32 v[28:29], v[12:13], v[26:27]
	v_sub_f32_e32 v13, v14, v213
	v_sub_f32_e32 v14, v30, v213
	v_pk_add_f32 v[28:29], v[28:29], v[28:29] op_sel_hi:[0,1]
	v_exp_f32_e32 v27, v14
	v_sub_f32_e32 v14, v15, v213
	v_exp_f32_e32 v13, v13
	v_exp_f32_e32 v28, v14
	v_sub_f32_e32 v14, v31, v213
	v_exp_f32_e32 v14, v14
	v_sub_f32_e32 v15, v16, v213
	v_exp_f32_e32 v63, v15
	v_sub_f32_e32 v15, v32, v213
	v_exp_f32_e32 v32, v15
	v_add_f32_e32 v15, v27, v13
	v_pk_add_f32 v[30:31], v[14:15], v[28:29]
	v_bitop3_b32 v2, v52, 15, v237 bitop3:0x48
	v_pk_add_f32 v[30:31], v[30:31], v[30:31] op_sel_hi:[0,1]
	v_sub_f32_e32 v15, v17, v213
	v_lshlrev_b32_e32 v2, 4, v2
	v_exp_f32_e32 v30, v15
	v_sub_f32_e32 v15, v33, v213
	v_or3_b32 v214, v214, s37, v2
	v_or_b32_e32 v2, s27, v53
	v_exp_f32_e32 v50, v15
	v_ashrrev_i32_e32 v3, 31, v2
	v_cvt_pk_bf16_f32 v179, v62, v4
	v_lshlrev_b64 v[2:3], 15, v[2:3]
	v_bitop3_b32 v4, v54, 7, v237 bitop3:0x48
	v_lshl_or_b32 v2, v4, 4, v2
	v_add_f32_e32 v51, v32, v63
	v_lshl_add_u64 v[216:217], v[2:3], 0, s[44:45]
	v_sub_u32_e32 v2, v236, v235
	v_mov_b64_e32 v[48:49], s[98:99]
	v_pk_add_f32 v[16:17], v[50:51], v[30:31]
	v_subrev_u32_e32 v2, s22, v2
	v_mov_b64_e32 v[36:37], s[86:87]
	v_mov_b64_e32 v[38:39], s[88:89]
	v_mov_b64_e32 v[40:41], s[90:91]
	v_mov_b64_e32 v[42:43], s[92:93]
	v_mov_b64_e32 v[44:45], s[94:95]
	v_mov_b64_e32 v[46:47], s[96:97]
	v_xor_b32_e32 v66, 0x80000000, v213
	v_add_f32_e32 v242, v16, v17
	v_cvt_pk_bf16_f32 v164, v5, v20
	v_cvt_pk_bf16_f32 v165, v7, v22
	v_cvt_pk_bf16_f32 v170, v9, v24
	v_cvt_pk_bf16_f32 v171, v11, v26
	v_cvt_pk_bf16_f32 v172, v13, v28
	v_cvt_pk_bf16_f32 v173, v63, v30
	v_cvt_pk_bf16_f32 v180, v19, v6
	v_cvt_pk_bf16_f32 v181, v21, v8
	v_cvt_pk_bf16_f32 v186, v23, v10
	v_cvt_pk_bf16_f32 v187, v25, v12
	v_cvt_pk_bf16_f32 v188, v27, v14
	v_cvt_pk_bf16_f32 v189, v32, v50
	v_subrev_u32_e32 v248, s21, v2
	v_mov_b64_e32 v[64:65], v[48:49]
	v_mov_b64_e32 v[18:19], v[34:35]
	v_mov_b64_e32 v[2:3], v[34:35]
	v_readlane_b32 s94, v255, 10
	v_readlane_b32 s90, v255, 12
	v_mov_b32_e32 v67, v66
	v_mov_b32_e32 v68, v66
	v_mov_b32_e32 v69, v66
	v_mov_b32_e32 v70, v66
	v_mov_b32_e32 v71, v66
	v_mov_b32_e32 v72, v66
	v_mov_b32_e32 v73, v66
	v_mov_b32_e32 v74, v66
	v_mov_b32_e32 v75, v66
	v_mov_b32_e32 v76, v66
	v_mov_b32_e32 v77, v66
	v_mov_b32_e32 v78, v66
	v_mov_b32_e32 v79, v66
	v_mov_b32_e32 v80, v66
	v_mov_b32_e32 v81, v66
	s_mov_b32 s21, 0
	v_mov_b32_e32 v166, 0
	v_mov_b32_e32 v167, 0
	v_mov_b32_e32 v168, 0
	v_mov_b32_e32 v169, 0
	v_mov_b32_e32 v174, 0
	v_mov_b32_e32 v175, 0
	v_mov_b32_e32 v176, 0
	v_mov_b32_e32 v177, 0
	v_mov_b32_e32 v182, 0
	v_mov_b32_e32 v183, 0
	v_mov_b32_e32 v184, 0
	v_mov_b32_e32 v185, 0
	v_mov_b32_e32 v190, 0
	v_mov_b32_e32 v191, 0
	v_mov_b32_e32 v192, 0
	v_mov_b32_e32 v193, 0
	v_mov_b64_e32 v[62:63], v[46:47]
	v_mov_b64_e32 v[60:61], v[44:45]
	v_mov_b64_e32 v[58:59], v[42:43]
	v_mov_b64_e32 v[56:57], v[40:41]
	v_mov_b64_e32 v[54:55], v[38:39]
	v_mov_b64_e32 v[52:53], v[36:37]
	v_mov_b64_e32 v[50:51], v[34:35]
	v_mov_b64_e32 v[20:21], v[36:37]
	v_mov_b64_e32 v[22:23], v[38:39]
	v_mov_b64_e32 v[24:25], v[40:41]
	v_mov_b64_e32 v[26:27], v[42:43]
	v_mov_b64_e32 v[28:29], v[44:45]
	v_mov_b64_e32 v[30:31], v[46:47]
	v_mov_b64_e32 v[32:33], v[48:49]
	v_mov_b64_e32 v[4:5], v[36:37]
	v_mov_b64_e32 v[6:7], v[38:39]
	v_mov_b64_e32 v[8:9], v[40:41]
	v_mov_b64_e32 v[10:11], v[42:43]
	v_mov_b64_e32 v[12:13], v[44:45]
	v_mov_b64_e32 v[14:15], v[46:47]
	v_mov_b64_e32 v[16:17], v[48:49]
	s_mov_b32 s33, 0x4000
	s_mov_b32 s48, 0
	s_mov_b32 s49, 0
	s_movk_i32 s92, 0x6e
	s_movk_i32 s93, 0xd0
	s_mov_b32 s57, 0x41000000
	v_readlane_b32 s95, v255, 11
	v_readlane_b32 s91, v255, 13
	s_add_u32 s80, s8, 0xd0c0000
	s_addc_u32 s81, s9, 0
	s_add_u32 s62, s8, 0xd0e0000
	s_addc_u32 s63, s9, 0
	s_add_u32 s96, s8, 0x15000100
	s_addc_u32 s97, s9, 0
	s_add_u32 s58, s8, 0x15200100
	s_addc_u32 s59, s9, 0
	s_add_u32 s50, s8, 0xd100000
	s_addc_u32 s51, s9, 0
	s_add_u32 s4, s8, 0xd120000
	s_addc_u32 s5, s9, 0
	s_add_u32 s0, s8, 0x15000180
	s_addc_u32 s1, s9, 0
	s_add_u32 s52, s8, 0x15200180
	s_addc_u32 s53, s9, 0
	v_add_u32_e32 v244, 0x8000, v244
	v_add_u32_e32 v245, 0x8000, v245
	v_add_u32_e32 v246, 0x8000, v246
	v_add_u32_e32 v247, 0x8000, v247
	ds_read_b128 v[202:205], v239 offset:16384
	ds_read_b128 v[194:197], v239 offset:24576
	ds_read_b128 v[198:201], v240 offset:16384
	ds_read_b128 v[206:209], v240 offset:24576

.LBB0_185:
	ds_read_b128 v[126:129], v244 offset:16384
	s_waitcnt lgkmcnt(1)
	v_mfma_f32_32x32x16_bf16 v[82:97], v[202:205], v[146:149], v[66:81]
	v_mfma_f32_32x32x16_bf16 v[98:113], v[194:197], v[146:149], v[66:81]
	ds_read_b128 v[114:117], v241 offset:16384
	v_mfma_f32_32x32x16_bf16 v[82:97], v[198:201], v[150:153], v[82:97]
	ds_read_b128 v[118:121], v241 offset:24576
	v_mfma_f32_32x32x16_bf16 v[98:113], v[206:209], v[150:153], v[98:113]
	ds_read_b128 v[122:125], v243 offset:16384
	s_waitcnt lgkmcnt(1)
	v_mfma_f32_32x32x16_bf16 v[82:97], v[114:117], v[154:157], v[82:97]
	ds_read_b128 v[114:117], v243 offset:24576
	v_mfma_f32_32x32x16_bf16 v[98:113], v[118:121], v[154:157], v[98:113]
	s_waitcnt lgkmcnt(0)
	v_mfma_f32_32x32x16_bf16 v[82:97], v[122:125], v[158:161], v[82:97]
	v_mfma_f32_32x32x16_bf16 v[98:113], v[114:117], v[158:161], v[98:113]
	s_nop 0
	ds_read_b128 v[122:125], v244 offset:20480
	ds_read_b128 v[118:121], v244 offset:24576
	ds_read_b128 v[114:117], v244 offset:28672
	s_add_i32 s22, s21, 64
	s_cmp_le_u32 s22, s20
	s_cbranch_scc0 .Lnear_u1e

.LBB0_196:
	s_waitcnt lgkmcnt(2)
	v_mfma_f32_32x32x16_bf16 v[18:33], v[118:121], v[186:189], v[18:33]
	ds_read_b128 v[198:201], v240 offset:32768
	v_exp_f32_e32 v118, v110
	v_exp_f32_e32 v119, v111
	v_add_f32_e32 v120, v122, v118
	v_add_f32_e32 v121, v123, v119
	v_cvt_pk_bf16_f32 v192, v118, v119
	v_mfma_f32_32x32x16_bf16 v[2:17], v[114:117], v[186:189], v[2:17]
	ds_read_b128 v[206:209], v240 offset:40960
	v_exp_f32_e32 v114, v112
	v_exp_f32_e32 v115, v113
	v_add_f32_e32 v116, v120, v114
	v_add_f32_e32 v117, v121, v115
	v_cvt_pk_bf16_f32 v193, v114, v115
	v_add_f32_e32 v212, v116, v117
	v_cmp_nge_f32_e32 vcc, s7, v212
	s_cbranch_vccnz .Lrare_u1e

.LBB0_225:
	ds_read_b128 v[126:129], v244 offset:32768
	s_waitcnt lgkmcnt(1)
	v_mfma_f32_32x32x16_bf16 v[82:97], v[202:205], v[146:149], v[66:81]
	v_mfma_f32_32x32x16_bf16 v[98:113], v[194:197], v[146:149], v[66:81]
	ds_read_b128 v[114:117], v241 offset:32768
	v_mfma_f32_32x32x16_bf16 v[82:97], v[198:201], v[150:153], v[82:97]
	ds_read_b128 v[118:121], v241 offset:40960
	v_mfma_f32_32x32x16_bf16 v[98:113], v[206:209], v[150:153], v[98:113]
	ds_read_b128 v[122:125], v243 offset:32768
	s_waitcnt lgkmcnt(1)
	v_mfma_f32_32x32x16_bf16 v[82:97], v[114:117], v[154:157], v[82:97]
	ds_read_b128 v[114:117], v243 offset:40960
	v_mfma_f32_32x32x16_bf16 v[98:113], v[118:121], v[154:157], v[98:113]
	s_waitcnt lgkmcnt(0)
	v_mfma_f32_32x32x16_bf16 v[82:97], v[122:125], v[158:161], v[82:97]
	v_mfma_f32_32x32x16_bf16 v[98:113], v[114:117], v[158:161], v[98:113]
	s_nop 0
	ds_read_b128 v[122:125], v244 offset:36864
	ds_read_b128 v[118:121], v244 offset:40960
	ds_read_b128 v[114:117], v244 offset:45056
	s_add_i32 s26, s21, 0x80
	s_cmp_le_u32 s26, s20
	s_cbranch_scc0 .Lnear_u1o

.LBB0_236:
	s_waitcnt lgkmcnt(2)
	v_mfma_f32_32x32x16_bf16 v[18:33], v[118:121], v[190:193], v[18:33]
	ds_read_b128 v[198:201], v240
	v_exp_f32_e32 v118, v110
	v_exp_f32_e32 v119, v111
	v_add_f32_e32 v120, v122, v118
	v_add_f32_e32 v121, v123, v119
	v_cvt_pk_bf16_f32 v188, v118, v119
	v_mfma_f32_32x32x16_bf16 v[2:17], v[114:117], v[190:193], v[2:17]
	ds_read_b128 v[206:209], v240 offset:8192
	v_exp_f32_e32 v114, v112
	v_exp_f32_e32 v115, v113
	v_add_f32_e32 v116, v120, v114
	v_add_f32_e32 v117, v121, v115
	v_cvt_pk_bf16_f32 v189, v114, v115
	v_add_f32_e32 v212, v116, v117
	v_cmp_nge_f32_e32 vcc, s7, v212
	s_cbranch_vccnz .Lrare_u1o

.Lr1u1_LBB0_185:
	ds_read_b128 v[126:129], v244 offset:49152
	s_waitcnt lgkmcnt(1)
	v_mfma_f32_32x32x16_bf16 v[82:97], v[202:205], v[146:149], v[66:81]
	v_mfma_f32_32x32x16_bf16 v[98:113], v[194:197], v[146:149], v[66:81]
	ds_read_b128 v[114:117], v241
	v_mfma_f32_32x32x16_bf16 v[82:97], v[198:201], v[150:153], v[82:97]
	ds_read_b128 v[118:121], v241 offset:8192
	v_mfma_f32_32x32x16_bf16 v[98:113], v[206:209], v[150:153], v[98:113]
	ds_read_b128 v[122:125], v243
	s_waitcnt lgkmcnt(1)
	v_mfma_f32_32x32x16_bf16 v[82:97], v[114:117], v[154:157], v[82:97]
	ds_read_b128 v[114:117], v243 offset:8192
	v_mfma_f32_32x32x16_bf16 v[98:113], v[118:121], v[154:157], v[98:113]
	s_waitcnt lgkmcnt(0)
	v_mfma_f32_32x32x16_bf16 v[82:97], v[122:125], v[158:161], v[82:97]
	v_mfma_f32_32x32x16_bf16 v[98:113], v[114:117], v[158:161], v[98:113]
	s_nop 0
	ds_read_b128 v[122:125], v244 offset:53248
	ds_read_b128 v[118:121], v244 offset:57344
	ds_read_b128 v[114:117], v244 offset:61440
	s_add_i32 s22, s21, 64
	s_cmp_le_u32 s22, s20
	s_cbranch_scc0 .Lr1u1_Lnear_u1e

.Lr1u1_LBB0_196:
	s_waitcnt lgkmcnt(2)
	v_mfma_f32_32x32x16_bf16 v[18:33], v[118:121], v[186:189], v[18:33]
	ds_read_b128 v[198:201], v240 offset:16384
	v_exp_f32_e32 v118, v110
	v_exp_f32_e32 v119, v111
	v_add_f32_e32 v120, v122, v118
	v_add_f32_e32 v121, v123, v119
	v_cvt_pk_bf16_f32 v192, v118, v119
	v_mfma_f32_32x32x16_bf16 v[2:17], v[114:117], v[186:189], v[2:17]
	ds_read_b128 v[206:209], v240 offset:24576
	v_exp_f32_e32 v114, v112
	v_exp_f32_e32 v115, v113
	v_add_f32_e32 v116, v120, v114
	v_add_f32_e32 v117, v121, v115
	v_cvt_pk_bf16_f32 v193, v114, v115
	v_add_f32_e32 v212, v116, v117
	v_cmp_nge_f32_e32 vcc, s7, v212
	s_cbranch_vccnz .Lr1u1_Lrare_u1e

.Lr1u1_LBB0_225:
	ds_read_b128 v[126:129], v244 offset:16384
	s_waitcnt lgkmcnt(1)
	v_mfma_f32_32x32x16_bf16 v[82:97], v[202:205], v[146:149], v[66:81]
	v_mfma_f32_32x32x16_bf16 v[98:113], v[194:197], v[146:149], v[66:81]
	ds_read_b128 v[114:117], v241 offset:16384
	v_mfma_f32_32x32x16_bf16 v[82:97], v[198:201], v[150:153], v[82:97]
	ds_read_b128 v[118:121], v241 offset:24576
	v_mfma_f32_32x32x16_bf16 v[98:113], v[206:209], v[150:153], v[98:113]
	ds_read_b128 v[122:125], v243 offset:16384
	s_waitcnt lgkmcnt(1)
	v_mfma_f32_32x32x16_bf16 v[82:97], v[114:117], v[154:157], v[82:97]
	ds_read_b128 v[114:117], v243 offset:24576
	v_mfma_f32_32x32x16_bf16 v[98:113], v[118:121], v[154:157], v[98:113]
	s_waitcnt lgkmcnt(0)
	v_mfma_f32_32x32x16_bf16 v[82:97], v[122:125], v[158:161], v[82:97]
	v_mfma_f32_32x32x16_bf16 v[98:113], v[114:117], v[158:161], v[98:113]
	s_nop 0
	ds_read_b128 v[122:125], v244 offset:20480
	ds_read_b128 v[118:121], v244 offset:24576
	ds_read_b128 v[114:117], v244 offset:28672
	s_add_i32 s26, s21, 0x80
	s_cmp_le_u32 s26, s20
	s_cbranch_scc0 .Lr1u1_Lnear_u1o

.Lr1u1_LBB0_236:
	s_waitcnt lgkmcnt(2)
	v_mfma_f32_32x32x16_bf16 v[18:33], v[118:121], v[190:193], v[18:33]
	ds_read_b128 v[198:201], v240 offset:32768
	v_exp_f32_e32 v118, v110
	v_exp_f32_e32 v119, v111
	v_add_f32_e32 v120, v122, v118
	v_add_f32_e32 v121, v123, v119
	v_cvt_pk_bf16_f32 v188, v118, v119
	v_mfma_f32_32x32x16_bf16 v[2:17], v[114:117], v[190:193], v[2:17]
	ds_read_b128 v[206:209], v240 offset:40960
	v_exp_f32_e32 v114, v112
	v_exp_f32_e32 v115, v113
	v_add_f32_e32 v116, v120, v114
	v_add_f32_e32 v117, v121, v115
	v_cvt_pk_bf16_f32 v189, v114, v115
	v_add_f32_e32 v212, v116, v117
	v_cmp_nge_f32_e32 vcc, s7, v212
	s_cbranch_vccnz .Lr1u1_Lrare_u1o

.Lr2u1_LBB0_185:
	ds_read_b128 v[126:129], v244 offset:32768
	s_waitcnt lgkmcnt(1)
	v_mfma_f32_32x32x16_bf16 v[82:97], v[202:205], v[146:149], v[66:81]
	v_mfma_f32_32x32x16_bf16 v[98:113], v[194:197], v[146:149], v[66:81]
	ds_read_b128 v[114:117], v241 offset:32768
	v_mfma_f32_32x32x16_bf16 v[82:97], v[198:201], v[150:153], v[82:97]
	ds_read_b128 v[118:121], v241 offset:40960
	v_mfma_f32_32x32x16_bf16 v[98:113], v[206:209], v[150:153], v[98:113]
	ds_read_b128 v[122:125], v243 offset:32768
	s_waitcnt lgkmcnt(1)
	v_mfma_f32_32x32x16_bf16 v[82:97], v[114:117], v[154:157], v[82:97]
	ds_read_b128 v[114:117], v243 offset:40960
	v_mfma_f32_32x32x16_bf16 v[98:113], v[118:121], v[154:157], v[98:113]
	s_waitcnt lgkmcnt(0)
	v_mfma_f32_32x32x16_bf16 v[82:97], v[122:125], v[158:161], v[82:97]
	v_mfma_f32_32x32x16_bf16 v[98:113], v[114:117], v[158:161], v[98:113]
	s_nop 0
	ds_read_b128 v[122:125], v244 offset:36864
	ds_read_b128 v[118:121], v244 offset:40960
	ds_read_b128 v[114:117], v244 offset:45056
	s_add_i32 s22, s21, 64
	s_cmp_le_u32 s22, s20
	s_cbranch_scc0 .Lr2u1_Lnear_u1e

.Lr2u1_LBB0_196:
	s_waitcnt lgkmcnt(2)
	v_mfma_f32_32x32x16_bf16 v[18:33], v[118:121], v[186:189], v[18:33]
	ds_read_b128 v[198:201], v240
	v_exp_f32_e32 v118, v110
	v_exp_f32_e32 v119, v111
	v_add_f32_e32 v120, v122, v118
	v_add_f32_e32 v121, v123, v119
	v_cvt_pk_bf16_f32 v192, v118, v119
	v_mfma_f32_32x32x16_bf16 v[2:17], v[114:117], v[186:189], v[2:17]
	ds_read_b128 v[206:209], v240 offset:8192
	v_exp_f32_e32 v114, v112
	v_exp_f32_e32 v115, v113
	v_add_f32_e32 v116, v120, v114
	v_add_f32_e32 v117, v121, v115
	v_cvt_pk_bf16_f32 v193, v114, v115
	v_add_f32_e32 v212, v116, v117
	v_cmp_nge_f32_e32 vcc, s7, v212
	s_cbranch_vccnz .Lr2u1_Lrare_u1e

.Lr2u1_LBB0_225:
	ds_read_b128 v[126:129], v244 offset:49152
	s_waitcnt lgkmcnt(1)
	v_mfma_f32_32x32x16_bf16 v[82:97], v[202:205], v[146:149], v[66:81]
	v_mfma_f32_32x32x16_bf16 v[98:113], v[194:197], v[146:149], v[66:81]
	ds_read_b128 v[114:117], v241
	v_mfma_f32_32x32x16_bf16 v[82:97], v[198:201], v[150:153], v[82:97]
	ds_read_b128 v[118:121], v241 offset:8192
	v_mfma_f32_32x32x16_bf16 v[98:113], v[206:209], v[150:153], v[98:113]
	ds_read_b128 v[122:125], v243
	s_waitcnt lgkmcnt(1)
	v_mfma_f32_32x32x16_bf16 v[82:97], v[114:117], v[154:157], v[82:97]
	ds_read_b128 v[114:117], v243 offset:8192
	v_mfma_f32_32x32x16_bf16 v[98:113], v[118:121], v[154:157], v[98:113]
	s_waitcnt lgkmcnt(0)
	v_mfma_f32_32x32x16_bf16 v[82:97], v[122:125], v[158:161], v[82:97]
	v_mfma_f32_32x32x16_bf16 v[98:113], v[114:117], v[158:161], v[98:113]
	s_nop 0
	ds_read_b128 v[122:125], v244 offset:53248
	ds_read_b128 v[118:121], v244 offset:57344
	ds_read_b128 v[114:117], v244 offset:61440
	s_add_i32 s26, s21, 0x80
	s_cmp_le_u32 s26, s20
	s_cbranch_scc0 .Lr2u1_Lnear_u1o

.Lr2u1_LBB0_236:
	s_waitcnt lgkmcnt(2)
	v_mfma_f32_32x32x16_bf16 v[18:33], v[118:121], v[190:193], v[18:33]
	ds_read_b128 v[198:201], v240 offset:16384
	v_exp_f32_e32 v118, v110
	v_exp_f32_e32 v119, v111
	v_add_f32_e32 v120, v122, v118
	v_add_f32_e32 v121, v123, v119
	v_cvt_pk_bf16_f32 v188, v118, v119
	v_mfma_f32_32x32x16_bf16 v[2:17], v[114:117], v[190:193], v[2:17]
	ds_read_b128 v[206:209], v240 offset:24576
	v_exp_f32_e32 v114, v112
	v_exp_f32_e32 v115, v113
	v_add_f32_e32 v116, v120, v114
	v_add_f32_e32 v117, v121, v115
	v_cvt_pk_bf16_f32 v189, v114, v115
	v_add_f32_e32 v212, v116, v117
	v_cmp_nge_f32_e32 vcc, s7, v212
	s_cbranch_vccnz .Lr2u1_Lrare_u1o

.LBB0_266:
	s_nop 6
	v_max_f32_e32 v0, v19, v19
	v_max_f32_e32 v39, v3, v3
	v_max_f32_e32 v0, v39, v0
	v_max3_f32 v0, v2, v18, v0
	v_max3_f32 v39, v20, v5, v21
	v_max3_f32 v0, v0, v4, v39
	v_max3_f32 v39, v22, v7, v23
	v_max3_f32 v0, v0, v6, v39
	v_max3_f32 v39, v24, v9, v25
	v_max3_f32 v0, v0, v8, v39
	v_max3_f32 v39, v26, v11, v27
	v_max3_f32 v0, v0, v10, v39
	v_max3_f32 v39, v28, v13, v29
	v_max3_f32 v0, v0, v12, v39
	v_max3_f32 v39, v30, v15, v31
	v_max3_f32 v0, v0, v14, v39
	v_max3_f32 v39, v32, v17, v33
	v_max3_f32 v0, v0, v16, v39
	v_mov_b32_e32 v39, v0
	s_nop 1
	v_permlane32_swap_b32_e32 v0, v39
	v_max_f32_e32 v39, v39, v39
	v_max_f32_e32 v0, v0, v0
	v_max_f32_e32 v213, v0, v39
	v_sub_f32_e32 v0, v2, v213
	v_exp_f32_e32 v40, v0
	v_sub_f32_e32 v0, v18, v213
	v_exp_f32_e32 v41, v0
	v_sub_f32_e32 v0, v3, v213
	v_sub_f32_e32 v2, v19, v213
	v_exp_f32_e32 v0, v0
	v_exp_f32_e32 v2, v2
	v_add_f32_e32 v3, v41, v40
	s_movk_i32 s27, 0x510
	v_cvt_pk_bf16_f32 v162, v40, v0
	v_pk_add_f32 v[18:19], v[2:3], v[0:1]
	v_sub_f32_e32 v3, v4, v213
	v_sub_f32_e32 v4, v20, v213
	v_pk_add_f32 v[18:19], v[18:19], v[18:19] op_sel_hi:[0,1]
	v_exp_f32_e32 v43, v4
	v_sub_f32_e32 v4, v5, v213
	v_exp_f32_e32 v3, v3
	v_exp_f32_e32 v18, v4
	v_sub_f32_e32 v4, v21, v213
	v_exp_f32_e32 v4, v4
	v_add_f32_e32 v5, v43, v3
	v_xad_u32 v0, v37, -1, v236
	v_cvt_pk_bf16_f32 v178, v41, v2
	v_pk_add_f32 v[20:21], v[4:5], v[18:19]
	v_sub_f32_e32 v5, v6, v213
	v_sub_f32_e32 v6, v22, v213
	v_pk_add_f32 v[20:21], v[20:21], v[20:21] op_sel_hi:[0,1]
	v_exp_f32_e32 v19, v6
	v_sub_f32_e32 v6, v7, v213
	v_exp_f32_e32 v5, v5
	v_exp_f32_e32 v20, v6
	v_sub_f32_e32 v6, v23, v213
	v_exp_f32_e32 v6, v6
	v_add_f32_e32 v7, v19, v5
	v_and_b32_e32 v0, 3, v0
	v_mov_b32_e32 v2, s31
	v_pk_add_f32 v[22:23], v[6:7], v[20:21]
	v_sub_f32_e32 v7, v8, v213
	v_sub_f32_e32 v8, v24, v213
	v_pk_add_f32 v[22:23], v[22:23], v[22:23] op_sel_hi:[0,1]
	v_exp_f32_e32 v21, v8
	v_sub_f32_e32 v8, v9, v213
	v_exp_f32_e32 v7, v7
	v_exp_f32_e32 v22, v8
	v_sub_f32_e32 v8, v25, v213
	v_exp_f32_e32 v8, v8
	v_add_f32_e32 v9, v21, v7
	s_add_i32 s20, s20, s56
	v_mad_u32_u24 v244, v0, s27, v2
	v_pk_add_f32 v[24:25], v[8:9], v[22:23]
	v_sub_f32_e32 v9, v10, v213
	v_sub_f32_e32 v10, v26, v213
	v_pk_add_f32 v[24:25], v[24:25], v[24:25] op_sel_hi:[0,1]
	v_exp_f32_e32 v23, v10
	v_sub_f32_e32 v10, v11, v213
	v_exp_f32_e32 v9, v9
	v_exp_f32_e32 v24, v10
	v_sub_f32_e32 v10, v27, v213
	v_exp_f32_e32 v10, v10
	v_add_f32_e32 v11, v23, v9
	v_add_u32_e32 v2, s20, v233
	v_cvt_pk_bf16_f32 v163, v3, v18
	v_pk_add_f32 v[26:27], v[10:11], v[24:25]
	v_sub_f32_e32 v11, v12, v213
	v_sub_f32_e32 v12, v28, v213
	v_pk_add_f32 v[26:27], v[26:27], v[26:27] op_sel_hi:[0,1]
	v_exp_f32_e32 v25, v12
	v_sub_f32_e32 v12, v13, v213
	v_exp_f32_e32 v11, v11
	v_exp_f32_e32 v26, v12
	v_sub_f32_e32 v12, v29, v213
	v_exp_f32_e32 v12, v12
	v_add_f32_e32 v13, v25, v11
	v_ashrrev_i32_e32 v3, 31, v2
	v_lshlrev_b64 v[2:3], 12, v[2:3]
	v_pk_add_f32 v[28:29], v[12:13], v[26:27]
	v_sub_f32_e32 v13, v14, v213
	v_sub_f32_e32 v14, v30, v213
	v_pk_add_f32 v[28:29], v[28:29], v[28:29] op_sel_hi:[0,1]
	v_exp_f32_e32 v27, v14
	v_sub_f32_e32 v14, v15, v213
	v_exp_f32_e32 v13, v13
	v_exp_f32_e32 v28, v14
	v_sub_f32_e32 v14, v31, v213
	v_exp_f32_e32 v14, v14
	v_sub_f32_e32 v15, v16, v213
	v_exp_f32_e32 v48, v15
	v_sub_f32_e32 v15, v32, v213
	v_exp_f32_e32 v32, v15
	v_add_f32_e32 v15, v27, v13
	v_pk_add_f32 v[30:31], v[14:15], v[28:29]
	v_and_b32_e32 v0, 15, v34
	v_pk_add_f32 v[30:31], v[30:31], v[30:31] op_sel_hi:[0,1]
	v_sub_f32_e32 v15, v17, v213
	v_or_b32_e32 v2, s37, v2
	v_lshlrev_b32_e32 v0, 4, v0
	s_add_i32 s21, s21, s36
	v_exp_f32_e32 v30, v15
	v_sub_f32_e32 v15, v33, v213
	v_lshl_add_u64 v[214:215], v[2:3], 0, v[0:1]
	v_add_u32_e32 v2, s21, v36
	v_and_b32_e32 v39, 7, v38
	v_bitop3_b32 v44, v38, v234, 7 bitop3:0x6c
	v_exp_f32_e32 v38, v15
	v_ashrrev_i32_e32 v3, 31, v2
	v_lshlrev_b64 v[2:3], 15, v[2:3]
	v_and_b32_e32 v0, 7, v35
	s_and_b32 s26, s47, 15
	v_lshl_or_b32 v2, v0, 4, v2
	v_sub_u32_e32 v0, v236, v235
	v_lshlrev_b32_e32 v42, 7, v235
	v_bitop3_b32 v45, v234, v39, 2 bitop3:0x36
	v_bitop3_b32 v46, v234, v39, 4 bitop3:0x36
	v_bitop3_b32 v47, v234, v39, 6 bitop3:0x36
	s_lshl_b32 s26, s26, 7
	v_add_f32_e32 v39, v32, v48
	v_cvt_pk_bf16_f32 v188, v27, v14
	v_subrev_u32_e32 v0, s28, v0
	v_mov_b32_e32 v14, v1
	v_mov_b32_e32 v15, v1
	s_lshl_b32 s17, s46, 1
	s_lshr_b32 s19, s16, 6
	v_pk_add_f32 v[16:17], v[38:39], v[30:31]
	v_cvt_pk_bf16_f32 v164, v5, v20
	v_cvt_pk_bf16_f32 v165, v7, v22
	v_cvt_pk_bf16_f32 v170, v9, v24
	v_cvt_pk_bf16_f32 v171, v11, v26
	v_cvt_pk_bf16_f32 v172, v13, v28
	v_cvt_pk_bf16_f32 v173, v48, v30
	v_cvt_pk_bf16_f32 v179, v43, v4
	v_cvt_pk_bf16_f32 v180, v19, v6
	v_cvt_pk_bf16_f32 v181, v21, v8
	v_cvt_pk_bf16_f32 v186, v23, v10
	v_cvt_pk_bf16_f32 v187, v25, v12
	v_cvt_pk_bf16_f32 v189, v32, v38
	v_lshl_or_b32 v245, v44, 4, v42
	v_lshl_or_b32 v246, v45, 4, v42
	v_lshl_or_b32 v247, v46, 4, v42
	v_lshl_or_b32 v248, v47, 4, v42
	v_lshl_add_u64 v[216:217], v[2:3], 0, s[44:45]
	v_subrev_u32_e32 v249, s26, v0
	v_mov_b32_e32 v0, v1
	v_mov_b32_e32 v2, v1
	v_mov_b32_e32 v3, v1
	v_mov_b32_e32 v4, v1
	v_mov_b32_e32 v5, v1
	v_mov_b32_e32 v6, v1
	v_mov_b32_e32 v7, v1
	v_mov_b32_e32 v8, v1
	v_mov_b32_e32 v9, v1
	v_mov_b32_e32 v10, v1
	v_mov_b32_e32 v11, v1
	v_mov_b32_e32 v12, v1
	v_mov_b32_e32 v13, v1
	v_mov_b64_e32 v[64:65], v[14:15]
	v_mov_b64_e32 v[48:49], v[14:15]
	v_mov_b64_e32 v[32:33], v[14:15]
	s_add_i32 s18, s17, 2
	s_add_i32 s19, s19, 1
	v_xor_b32_e32 v66, 0x80000000, v213
	v_add_f32_e32 v243, v16, v17
	v_mov_b64_e32 v[62:63], v[12:13]
	v_mov_b64_e32 v[60:61], v[10:11]
	v_mov_b64_e32 v[58:59], v[8:9]
	v_mov_b64_e32 v[56:57], v[6:7]
	v_mov_b64_e32 v[54:55], v[4:5]
	v_mov_b64_e32 v[52:53], v[2:3]
	v_mov_b64_e32 v[50:51], v[0:1]
	v_mov_b64_e32 v[46:47], v[12:13]
	v_mov_b64_e32 v[44:45], v[10:11]
	v_mov_b64_e32 v[42:43], v[8:9]
	v_mov_b64_e32 v[40:41], v[6:7]
	v_mov_b64_e32 v[38:39], v[4:5]
	v_mov_b64_e32 v[36:37], v[2:3]
	v_mov_b64_e32 v[34:35], v[0:1]
	v_mov_b64_e32 v[30:31], v[12:13]
	v_mov_b64_e32 v[28:29], v[10:11]
	v_mov_b64_e32 v[26:27], v[8:9]
	v_mov_b64_e32 v[24:25], v[6:7]
	v_mov_b64_e32 v[22:23], v[4:5]
	v_mov_b64_e32 v[20:21], v[2:3]
	v_mov_b64_e32 v[18:19], v[0:1]
	v_mov_b64_e32 v[16:17], v[14:15]
	s_mov_b32 s22, 1
	s_mov_b32 s23, 0x8000
	s_min_u32 s19, s18, s19
	v_mov_b32_e32 v67, v66
	v_mov_b32_e32 v68, v66
	v_mov_b32_e32 v69, v66
	v_mov_b32_e32 v70, v66
	v_mov_b32_e32 v71, v66
	v_mov_b32_e32 v72, v66
	v_mov_b32_e32 v73, v66
	v_mov_b32_e32 v74, v66
	v_mov_b32_e32 v75, v66
	v_mov_b32_e32 v76, v66
	v_mov_b32_e32 v77, v66
	v_mov_b32_e32 v78, v66
	v_mov_b32_e32 v79, v66
	v_mov_b32_e32 v80, v66
	v_mov_b32_e32 v81, v66
	s_mov_b32 s28, 0
	s_movk_i32 s20, 0xf0
	v_mov_b32_e32 v166, 0
	v_mov_b32_e32 v167, 0
	v_mov_b32_e32 v168, 0
	v_mov_b32_e32 v169, 0
	v_mov_b32_e32 v174, 0
	v_mov_b32_e32 v175, 0
	v_mov_b32_e32 v176, 0
	v_mov_b32_e32 v177, 0
	v_mov_b32_e32 v182, 0
	v_mov_b32_e32 v183, 0
	v_mov_b32_e32 v184, 0
	v_mov_b32_e32 v185, 0
	v_mov_b32_e32 v190, 0
	v_mov_b32_e32 v191, 0
	v_mov_b32_e32 v192, 0
	v_mov_b32_e32 v193, 0
	v_mov_b64_e32 v[14:15], v[12:13]
	v_mov_b64_e32 v[12:13], v[10:11]
	v_mov_b64_e32 v[10:11], v[8:9]
	v_mov_b64_e32 v[8:9], v[6:7]
	v_mov_b64_e32 v[6:7], v[4:5]
	v_mov_b64_e32 v[4:5], v[2:3]
	v_mov_b64_e32 v[2:3], v[0:1]
	s_mov_b32 s31, 0x4000
	s_mov_b32 s33, 0
	v_add_u32_e32 v245, 0x8000, v245
	v_add_u32_e32 v246, 0x8000, v246
	v_add_u32_e32 v247, 0x8000, v247
	v_add_u32_e32 v248, 0x8000, v248
	ds_read_b128 v[202:205], v239 offset:16384
	ds_read_b128 v[194:197], v239 offset:24576
	ds_read_b128 v[198:201], v240 offset:16384
	ds_read_b128 v[206:209], v240 offset:24576

.LBB0_288:
	ds_read_b128 v[126:129], v245 offset:16384
	s_waitcnt lgkmcnt(1)
	v_mfma_f32_32x32x16_bf16 v[82:97], v[202:205], v[146:149], v[66:81]
	v_mfma_f32_32x32x16_bf16 v[98:113], v[194:197], v[146:149], v[66:81]
	ds_read_b128 v[114:117], v241 offset:16384
	v_mfma_f32_32x32x16_bf16 v[82:97], v[198:201], v[150:153], v[82:97]
	ds_read_b128 v[118:121], v241 offset:24576
	v_mfma_f32_32x32x16_bf16 v[98:113], v[206:209], v[150:153], v[98:113]
	ds_read_b128 v[122:125], v242 offset:16384
	s_waitcnt lgkmcnt(1)
	v_mfma_f32_32x32x16_bf16 v[82:97], v[114:117], v[154:157], v[82:97]
	ds_read_b128 v[114:117], v242 offset:24576
	v_mfma_f32_32x32x16_bf16 v[98:113], v[118:121], v[154:157], v[98:113]
	s_waitcnt lgkmcnt(0)
	v_mfma_f32_32x32x16_bf16 v[82:97], v[122:125], v[158:161], v[82:97]
	v_mfma_f32_32x32x16_bf16 v[98:113], v[114:117], v[158:161], v[98:113]
	s_nop 0
	ds_read_b128 v[122:125], v245 offset:20480
	ds_read_b128 v[118:121], v245 offset:24576
	ds_read_b128 v[114:117], v245 offset:28672
	s_cmp_le_u32 s20, s16
	s_cbranch_scc0 .Lnear_u2e

.LBB0_299:
	s_waitcnt lgkmcnt(2)
	v_mfma_f32_32x32x16_bf16 v[18:33], v[118:121], v[186:189], v[18:33]
	ds_read_b128 v[198:201], v240 offset:32768
	v_exp_f32_e32 v118, v110
	v_exp_f32_e32 v119, v111
	v_add_f32_e32 v0, v0, v118
	v_add_f32_e32 v120, v122, v119
	v_cvt_pk_bf16_f32 v192, v118, v119
	v_mfma_f32_32x32x16_bf16 v[2:17], v[114:117], v[186:189], v[2:17]
	ds_read_b128 v[206:209], v240 offset:40960
	v_exp_f32_e32 v114, v112
	v_exp_f32_e32 v115, v113
	v_add_f32_e32 v0, v0, v114
	v_add_f32_e32 v116, v120, v115
	v_cvt_pk_bf16_f32 v193, v114, v115
	v_add_f32_e32 v212, v0, v116
	v_cmp_nge_f32_e32 vcc, s7, v212
	s_cbranch_vccnz .Lrare_u2e

.LBB0_328:
	ds_read_b128 v[126:129], v245 offset:32768
	s_waitcnt lgkmcnt(1)
	v_mfma_f32_32x32x16_bf16 v[82:97], v[202:205], v[146:149], v[66:81]
	v_mfma_f32_32x32x16_bf16 v[98:113], v[194:197], v[146:149], v[66:81]
	ds_read_b128 v[114:117], v241 offset:32768
	v_mfma_f32_32x32x16_bf16 v[82:97], v[198:201], v[150:153], v[82:97]
	ds_read_b128 v[118:121], v241 offset:40960
	v_mfma_f32_32x32x16_bf16 v[98:113], v[206:209], v[150:153], v[98:113]
	ds_read_b128 v[122:125], v242 offset:32768
	s_waitcnt lgkmcnt(1)
	v_mfma_f32_32x32x16_bf16 v[82:97], v[114:117], v[154:157], v[82:97]
	ds_read_b128 v[114:117], v242 offset:40960
	v_mfma_f32_32x32x16_bf16 v[98:113], v[118:121], v[154:157], v[98:113]
	s_waitcnt lgkmcnt(0)
	v_mfma_f32_32x32x16_bf16 v[82:97], v[122:125], v[158:161], v[82:97]
	v_mfma_f32_32x32x16_bf16 v[98:113], v[114:117], v[158:161], v[98:113]
	s_nop 0
	ds_read_b128 v[122:125], v245 offset:36864
	ds_read_b128 v[118:121], v245 offset:40960
	ds_read_b128 v[114:117], v245 offset:45056
	s_add_i32 s26, s20, 64
	s_cmp_le_u32 s26, s16
	s_cbranch_scc0 .Lnear_u2o

.LBB0_339:
	s_waitcnt lgkmcnt(2)
	v_mfma_f32_32x32x16_bf16 v[18:33], v[118:121], v[190:193], v[18:33]
	ds_read_b128 v[198:201], v240
	v_exp_f32_e32 v118, v110
	v_exp_f32_e32 v119, v111
	v_add_f32_e32 v0, v0, v118
	v_add_f32_e32 v120, v122, v119
	v_cvt_pk_bf16_f32 v188, v118, v119
	v_mfma_f32_32x32x16_bf16 v[2:17], v[114:117], v[190:193], v[2:17]
	ds_read_b128 v[206:209], v240 offset:8192
	v_exp_f32_e32 v114, v112
	v_exp_f32_e32 v115, v113
	v_add_f32_e32 v0, v0, v114
	v_add_f32_e32 v116, v120, v115
	v_cvt_pk_bf16_f32 v189, v114, v115
	v_add_f32_e32 v212, v0, v116
	v_cmp_nge_f32_e32 vcc, s7, v212
	s_cbranch_vccnz .Lrare_u2o

.Lr1u2_LBB0_288:
	ds_read_b128 v[126:129], v245 offset:49152
	s_waitcnt lgkmcnt(1)
	v_mfma_f32_32x32x16_bf16 v[82:97], v[202:205], v[146:149], v[66:81]
	v_mfma_f32_32x32x16_bf16 v[98:113], v[194:197], v[146:149], v[66:81]
	ds_read_b128 v[114:117], v241
	v_mfma_f32_32x32x16_bf16 v[82:97], v[198:201], v[150:153], v[82:97]
	ds_read_b128 v[118:121], v241 offset:8192
	v_mfma_f32_32x32x16_bf16 v[98:113], v[206:209], v[150:153], v[98:113]
	ds_read_b128 v[122:125], v242
	s_waitcnt lgkmcnt(1)
	v_mfma_f32_32x32x16_bf16 v[82:97], v[114:117], v[154:157], v[82:97]
	ds_read_b128 v[114:117], v242 offset:8192
	v_mfma_f32_32x32x16_bf16 v[98:113], v[118:121], v[154:157], v[98:113]
	s_waitcnt lgkmcnt(0)
	v_mfma_f32_32x32x16_bf16 v[82:97], v[122:125], v[158:161], v[82:97]
	v_mfma_f32_32x32x16_bf16 v[98:113], v[114:117], v[158:161], v[98:113]
	s_nop 0
	ds_read_b128 v[122:125], v245 offset:53248
	ds_read_b128 v[118:121], v245 offset:57344
	ds_read_b128 v[114:117], v245 offset:61440
	s_cmp_le_u32 s20, s16
	s_cbranch_scc0 .Lr1u2_Lnear_u2e

.Lr1u2_LBB0_299:
	s_waitcnt lgkmcnt(2)
	v_mfma_f32_32x32x16_bf16 v[18:33], v[118:121], v[186:189], v[18:33]
	ds_read_b128 v[198:201], v240 offset:16384
	v_exp_f32_e32 v118, v110
	v_exp_f32_e32 v119, v111
	v_add_f32_e32 v0, v0, v118
	v_add_f32_e32 v120, v122, v119
	v_cvt_pk_bf16_f32 v192, v118, v119
	v_mfma_f32_32x32x16_bf16 v[2:17], v[114:117], v[186:189], v[2:17]
	ds_read_b128 v[206:209], v240 offset:24576
	v_exp_f32_e32 v114, v112
	v_exp_f32_e32 v115, v113
	v_add_f32_e32 v0, v0, v114
	v_add_f32_e32 v116, v120, v115
	v_cvt_pk_bf16_f32 v193, v114, v115
	v_add_f32_e32 v212, v0, v116
	v_cmp_nge_f32_e32 vcc, s7, v212
	s_cbranch_vccnz .Lr1u2_Lrare_u2e

.Lr1u2_LBB0_328:
	ds_read_b128 v[126:129], v245 offset:16384
	s_waitcnt lgkmcnt(1)
	v_mfma_f32_32x32x16_bf16 v[82:97], v[202:205], v[146:149], v[66:81]
	v_mfma_f32_32x32x16_bf16 v[98:113], v[194:197], v[146:149], v[66:81]
	ds_read_b128 v[114:117], v241 offset:16384
	v_mfma_f32_32x32x16_bf16 v[82:97], v[198:201], v[150:153], v[82:97]
	ds_read_b128 v[118:121], v241 offset:24576
	v_mfma_f32_32x32x16_bf16 v[98:113], v[206:209], v[150:153], v[98:113]
	ds_read_b128 v[122:125], v242 offset:16384
	s_waitcnt lgkmcnt(1)
	v_mfma_f32_32x32x16_bf16 v[82:97], v[114:117], v[154:157], v[82:97]
	ds_read_b128 v[114:117], v242 offset:24576
	v_mfma_f32_32x32x16_bf16 v[98:113], v[118:121], v[154:157], v[98:113]
	s_waitcnt lgkmcnt(0)
	v_mfma_f32_32x32x16_bf16 v[82:97], v[122:125], v[158:161], v[82:97]
	v_mfma_f32_32x32x16_bf16 v[98:113], v[114:117], v[158:161], v[98:113]
	s_nop 0
	ds_read_b128 v[122:125], v245 offset:20480
	ds_read_b128 v[118:121], v245 offset:24576
	ds_read_b128 v[114:117], v245 offset:28672
	s_add_i32 s26, s20, 64
	s_cmp_le_u32 s26, s16
	s_cbranch_scc0 .Lr1u2_Lnear_u2o

.Lr1u2_LBB0_339:
	s_waitcnt lgkmcnt(2)
	v_mfma_f32_32x32x16_bf16 v[18:33], v[118:121], v[190:193], v[18:33]
	ds_read_b128 v[198:201], v240 offset:32768
	v_exp_f32_e32 v118, v110
	v_exp_f32_e32 v119, v111
	v_add_f32_e32 v0, v0, v118
	v_add_f32_e32 v120, v122, v119
	v_cvt_pk_bf16_f32 v188, v118, v119
	v_mfma_f32_32x32x16_bf16 v[2:17], v[114:117], v[190:193], v[2:17]
	ds_read_b128 v[206:209], v240 offset:40960
	v_exp_f32_e32 v114, v112
	v_exp_f32_e32 v115, v113
	v_add_f32_e32 v0, v0, v114
	v_add_f32_e32 v116, v120, v115
	v_cvt_pk_bf16_f32 v189, v114, v115
	v_add_f32_e32 v212, v0, v116
	v_cmp_nge_f32_e32 vcc, s7, v212
	s_cbranch_vccnz .Lr1u2_Lrare_u2o

.Lr2u2_LBB0_288:
	ds_read_b128 v[126:129], v245 offset:32768
	s_waitcnt lgkmcnt(1)
	v_mfma_f32_32x32x16_bf16 v[82:97], v[202:205], v[146:149], v[66:81]
	v_mfma_f32_32x32x16_bf16 v[98:113], v[194:197], v[146:149], v[66:81]
	ds_read_b128 v[114:117], v241 offset:32768
	v_mfma_f32_32x32x16_bf16 v[82:97], v[198:201], v[150:153], v[82:97]
	ds_read_b128 v[118:121], v241 offset:40960
	v_mfma_f32_32x32x16_bf16 v[98:113], v[206:209], v[150:153], v[98:113]
	ds_read_b128 v[122:125], v242 offset:32768
	s_waitcnt lgkmcnt(1)
	v_mfma_f32_32x32x16_bf16 v[82:97], v[114:117], v[154:157], v[82:97]
	ds_read_b128 v[114:117], v242 offset:40960
	v_mfma_f32_32x32x16_bf16 v[98:113], v[118:121], v[154:157], v[98:113]
	s_waitcnt lgkmcnt(0)
	v_mfma_f32_32x32x16_bf16 v[82:97], v[122:125], v[158:161], v[82:97]
	v_mfma_f32_32x32x16_bf16 v[98:113], v[114:117], v[158:161], v[98:113]
	s_nop 0
	ds_read_b128 v[122:125], v245 offset:36864
	ds_read_b128 v[118:121], v245 offset:40960
	ds_read_b128 v[114:117], v245 offset:45056
	s_cmp_le_u32 s20, s16
	s_cbranch_scc0 .Lr2u2_Lnear_u2e

.Lr2u2_LBB0_299:
	s_waitcnt lgkmcnt(2)
	v_mfma_f32_32x32x16_bf16 v[18:33], v[118:121], v[186:189], v[18:33]
	ds_read_b128 v[198:201], v240
	v_exp_f32_e32 v118, v110
	v_exp_f32_e32 v119, v111
	v_add_f32_e32 v0, v0, v118
	v_add_f32_e32 v120, v122, v119
	v_cvt_pk_bf16_f32 v192, v118, v119
	v_mfma_f32_32x32x16_bf16 v[2:17], v[114:117], v[186:189], v[2:17]
	ds_read_b128 v[206:209], v240 offset:8192
	v_exp_f32_e32 v114, v112
	v_exp_f32_e32 v115, v113
	v_add_f32_e32 v0, v0, v114
	v_add_f32_e32 v116, v120, v115
	v_cvt_pk_bf16_f32 v193, v114, v115
	v_add_f32_e32 v212, v0, v116
	v_cmp_nge_f32_e32 vcc, s7, v212
	s_cbranch_vccnz .Lr2u2_Lrare_u2e

.Lr2u2_LBB0_328:
	ds_read_b128 v[126:129], v245 offset:49152
	s_waitcnt lgkmcnt(1)
	v_mfma_f32_32x32x16_bf16 v[82:97], v[202:205], v[146:149], v[66:81]
	v_mfma_f32_32x32x16_bf16 v[98:113], v[194:197], v[146:149], v[66:81]
	ds_read_b128 v[114:117], v241
	v_mfma_f32_32x32x16_bf16 v[82:97], v[198:201], v[150:153], v[82:97]
	ds_read_b128 v[118:121], v241 offset:8192
	v_mfma_f32_32x32x16_bf16 v[98:113], v[206:209], v[150:153], v[98:113]
	ds_read_b128 v[122:125], v242
	s_waitcnt lgkmcnt(1)
	v_mfma_f32_32x32x16_bf16 v[82:97], v[114:117], v[154:157], v[82:97]
	ds_read_b128 v[114:117], v242 offset:8192
	v_mfma_f32_32x32x16_bf16 v[98:113], v[118:121], v[154:157], v[98:113]
	s_waitcnt lgkmcnt(0)
	v_mfma_f32_32x32x16_bf16 v[82:97], v[122:125], v[158:161], v[82:97]
	v_mfma_f32_32x32x16_bf16 v[98:113], v[114:117], v[158:161], v[98:113]
	s_nop 0
	ds_read_b128 v[122:125], v245 offset:53248
	ds_read_b128 v[118:121], v245 offset:57344
	ds_read_b128 v[114:117], v245 offset:61440
	s_add_i32 s26, s20, 64
	s_cmp_le_u32 s26, s16
	s_cbranch_scc0 .Lr2u2_Lnear_u2o

.Lr2u2_LBB0_339:
	s_waitcnt lgkmcnt(2)
	v_mfma_f32_32x32x16_bf16 v[18:33], v[118:121], v[190:193], v[18:33]
	ds_read_b128 v[198:201], v240 offset:16384
	v_exp_f32_e32 v118, v110
	v_exp_f32_e32 v119, v111
	v_add_f32_e32 v0, v0, v118
	v_add_f32_e32 v120, v122, v119
	v_cvt_pk_bf16_f32 v188, v118, v119
	v_mfma_f32_32x32x16_bf16 v[2:17], v[114:117], v[190:193], v[2:17]
	ds_read_b128 v[206:209], v240 offset:24576
	v_exp_f32_e32 v114, v112
	v_exp_f32_e32 v115, v113
	v_add_f32_e32 v0, v0, v114
	v_add_f32_e32 v116, v120, v115
	v_cvt_pk_bf16_f32 v189, v114, v115
	v_add_f32_e32 v212, v0, v116
	v_cmp_nge_f32_e32 vcc, s7, v212
	s_cbranch_vccnz .Lr2u2_Lrare_u2o
